# loader waves keep the 8 loop-invariant ks=1 LoRA B-fragments in registers across the chunk loop (no per-chunk dependent LDS re-reads)
# speedup vs baseline: 1.0165x; 1.0151x over previous
; #define LAS __attribute__((address_space(3)))
; __device__ __forceinline__ void phase_scan(const Params& p, LAS unsigned char* lds) {
;     ...
;         const int pw_ = wave & 3, s_sub = lane >> 3, c8 = (lane & 7) * 8, s_l = 8 * pw_ + s_sub;
;         h16x8 mu_r8, mu_k8, mu_v8, mu_w8, mu_a8; f32x2 w0r[4], a0r[4], kkr[4], kar[4], omk[4], rkr[4];
; #pragma unroll
;         for (int e = 0; e < 8; ++e) { mu_r8[e] = (h16)mu[64 * h + c8 + e]; mu_k8[e] = (h16)mu[1024 + 64 * h + c8 + e]; mu_v8[e] = (h16)mu[2048 + 64 * h + c8 + e]; mu_w8[e] = (h16)mu[3072 + c8 + e]; mu_a8[e] = (h16)mu[3136 + c8 + e];
;             w0r[e >> 1][e & 1] = w0[c8 + e]; a0r[e >> 1][e & 1] = a0[c8 + e]; kkr[e >> 1][e & 1] = kkw[c8 + e]; kar[e >> 1][e & 1] = kaw[c8 + e]; omk[e >> 1][e & 1] = 1.f - kaw[c8 + e]; rkr[e >> 1][e & 1] = rkw[c8 + e]; }
;         f32x2 S01 = {0.f, 0.f}, S23 = {0.f, 0.f};
;         const int srow = 4 * (wave & 3) + (lane >> 4), j0 = 4 * (lane & 15);
;         const h16x8 z8 = {0, 0, 0, 0, 0, 0, 0, 0};
;         h16x8 pr, pk, pv, pw, pa, qr_, qk_, qv_, qw_, qa_;
;         const h16 *pcA, *pcB, *ppA, *ppB;
;         { const int t0_ = dir ? (SEQ - 1 - s_l) : s_l; pcA = PC + (size_t)(b * SEQ + t0_) * 3200 + c8 + 64 * h; pcB = pcA + 2048 - 64 * h;
;           const long po_ = (s_l > 0) ? (dir ? 3200 : -3200) : 0; ppA = pcA + po_; ppB = pcB + po_; }
;         const long cstride_ = dir ? -32 * 3200 : 32 * 3200;
;     ...
;         if (wave >= 4) { SCAN_LOAD_RAW(); if (s_l == 0) { qr_ = z8; qk_ = z8; qv_ = z8; qw_ = z8; qa_ = z8; } }
;         __syncthreads();
;     ...
;                     for (int ks = 0; ks < 2; ++ks) {
;                         const h16x8 atw = *(const LAS h16x8*)(TWp + (lane & 7) * 72 + 32 * ks + 8 * (lane >> 4));
;                         const h16x8 aqa = *(const LAS h16x8*)(QAp + (lane & 7) * 72 + 32 * ks + 8 * (lane >> 4));
; #pragma unroll
;                         for (int ct = 0; ct < 4; ++ct) {
;                             const h16x8 bw = *(const LAS h16x8*)(w2T + (16 * ct + (lane & 15)) * 72 + 32 * ks + 8 * (lane >> 4));
;                             const h16x8 ba = *(const LAS h16x8*)(a2T + (16 * ct + (lane & 15)) * 72 + 32 * ks + 8 * (lane >> 4));
.LBB0_601:
	s_or_b64 exec, exec, s[10:11]
	s_waitcnt vmcnt(16)
	v_cvt_f16_f32_e32 v64, v64
	s_waitcnt vmcnt(13)
	v_cvt_f16_f32_e32 v68, v94
	v_cvt_f16_f32_e32 v0, v60
	s_waitcnt vmcnt(11)
	v_cvt_f16_f32_e32 v69, v98
	v_cvt_f16_f32_e32 v3, v90
	v_cvt_pk_f16_f32 v65, v65, v66
	v_cvt_pk_f16_f32 v90, v95, v96
	v_cvt_pk_f16_f32 v61, v61, v62
	v_pack_b32_f16 v62, v64, v65
	v_pack_b32_f16 v64, v68, v90
	v_cvt_pk_f16_f32 v68, v99, v100
	s_lshl_b64 s[48:49], s[12:13], 25
	s_lshl_b64 s[10:11], s[12:13], 20
	s_bfe_u32 s15, s78, 0x20003
	v_pack_b32_f16 v2, v0, v61
	v_cvt_pk_f16_f32 v0, v91, v92
	v_pack_b32_f16 v66, v69, v68
	v_cvt_pk_f16_f32 v69, v63, v74
	v_cvt_pk_f16_f32 v74, v93, v82
	s_waitcnt vmcnt(10)
	v_cvt_pk_f16_f32 v78, v101, v78
	v_cvt_pk_f16_f32 v75, v75, v76
	v_pack_b32_f16 v60, v3, v0
	v_alignbit_b32 v3, v69, v61, 16
	v_alignbit_b32 v61, v74, v0, 16
	v_cvt_pk_f16_f32 v0, v67, v70
	v_alignbit_b32 v67, v78, v68, 16
	v_alignbit_b32 v68, v75, v69, 16
	v_cvt_f16_f32_e32 v69, v77
	s_add_u32 s48, s68, s48
	s_addc_u32 s49, s69, s49
	s_add_u32 s34, s31, s10
	s_addc_u32 s35, s33, s11
	v_alignbit_b32 v69, v69, v75, 16
	v_cvt_f16_f32_e32 v75, v89
	s_add_u32 s54, s48, s20
	v_cvt_pk_f16_f32 v77, v79, v80
	s_addc_u32 s55, s49, 0
	s_lshl_b32 s14, s14, 2
	v_cvt_pk_f16_f32 v83, v83, v84
	v_cvt_pk_f16_f32 v84, v71, v72
	v_alignbit_b32 v76, v77, v78, 16
	v_cvt_f16_f32_e32 v71, v85
	v_cvt_f16_f32_e32 v73, v73
	v_cvt_f16_f32_e32 v78, v81
	s_add_u32 s52, s34, s14
	v_alignbit_b32 v63, v0, v65, 16
	v_cvt_pk_f16_f32 v82, v97, v86
	v_alignbit_b32 v72, v84, v0, 16
	v_cvt_pk_f16_f32 v0, v87, v88
	s_addc_u32 s53, s35, 0
	s_lshl_b32 s80, s15, 4
	s_lshl_b32 s14, s15, 5
	v_alignbit_b32 v70, v83, v74, 16
	v_alignbit_b32 v74, v0, v82, 16
	v_alignbit_b32 v75, v75, v0, 16
	v_or_b32_e32 v0, s15, v133
	s_add_u32 s14, s54, s14
	v_cmp_eq_u32_e64 s[10:11], s15, v176
	v_cmp_eq_u32_e64 s[12:13], 0, v0
	s_addc_u32 s15, s55, 0
	v_mov_b32_e32 v143, v1
	v_mov_b32_e32 v0, v1
	s_waitcnt vmcnt(2)
	v_pk_add_f32 v[154:155], v[48:49], 1.0 op_sel_hi:[1,0] neg_lo:[1,0] neg_hi:[1,0]
	v_pk_add_f32 v[156:157], v[50:51], 1.0 op_sel_hi:[1,0] neg_lo:[1,0] neg_hi:[1,0]
	v_alignbit_b32 v65, v82, v90, 16
	v_pk_add_f32 v[158:159], v[44:45], 1.0 op_sel_hi:[1,0] neg_lo:[1,0] neg_hi:[1,0]
	v_alignbit_b32 v71, v71, v83, 16
	v_alignbit_b32 v73, v73, v84, 16
	v_alignbit_b32 v77, v78, v77, 16
	v_pk_add_f32 v[160:161], v[46:47], 1.0 op_sel_hi:[1,0] neg_lo:[1,0] neg_hi:[1,0]
	s_waitcnt lgkmcnt(0)
	s_barrier
	v_lshl_add_u64 v[162:163], s[14:15], 0, v[142:143]
	s_mov_b32 s81, -1
	s_movk_i32 s82, 0xfc00
	v_mov_b32_e32 v143, v191
	v_mov_b32_e32 v145, v169
	v_mov_b64_e32 v[166:167], v[0:1]
	v_mov_b64_e32 v[164:165], v[0:1]
	s_cmp_eq_u64 s[0:1], 0
	s_cbranch_scc1 .Lhoist_skip
	ds_read_b128 v[132:135], v183 offset:64
	ds_read_b128 v[136:139], v183 offset:9280
	ds_read_b128 v[164:167], v183 offset:2368
	ds_read_b128 v[184:187], v183 offset:11584
	ds_read_b128 v[188:191], v183 offset:4672
	ds_read_b128 v[192:195], v183 offset:6976
	ds_read_b128 v[196:199], v183 offset:13888
	ds_read_b128 v[246:249], v183 offset:16192
	s_waitcnt lgkmcnt(0)
.Lhoist_skip:
	s_branch .LBB0_604
.LBB0_602:
	s_waitcnt vmcnt(2)
	v_mov_b64_e32 v[124:125], v[84:85]
	v_mov_b64_e32 v[120:121], v[92:93]
	v_mov_b64_e32 v[116:117], v[100:101]
	v_mov_b64_e32 v[112:113], v[80:81]
	v_mov_b64_e32 v[108:109], v[88:89]
	v_mov_b64_e32 v[104:105], v[96:97]
	v_mov_b64_e32 v[122:123], v[82:83]
	v_mov_b64_e32 v[118:119], v[90:91]
	v_mov_b64_e32 v[114:115], v[98:99]
	v_mov_b64_e32 v[110:111], v[78:79]
	v_mov_b64_e32 v[106:107], v[86:87]
	v_mov_b64_e32 v[102:103], v[94:95]

; #define LAS __attribute__((address_space(3)))
; #define SCAN_LOAD(chn) SCAN_LOAD_RAW()
; __device__ __forceinline__ void phase_scan(const Params& p, LAS unsigned char* lds) {
;     ...
;                     { unsigned m1u_ = 0xBC00BC00u; asm volatile("" : "+s"(m1u_));
;                       typedef unsigned u32x4_ __attribute__((ext_vector_type(4))); const u32x4_ m1v_ = {m1u_, m1u_, m1u_, m1u_}; const h16x8 m1_ = __builtin_bit_cast(h16x8, m1v_);
;                       const h16x8 r8 = pr + mu_r8 * (pr * m1_ + qr_), k8 = pk + mu_k8 * (pk * m1_ + qk_), v8 = pv + mu_v8 * (pv * m1_ + qv_);
;                       const h16x8 w8 = pw + mu_w8 * (pw * m1_ + qw_), a8 = pa + mu_a8 * (pa * m1_ + qa_);
;                       h16x8 tw8;
; #pragma unroll
;                       for (int pi = 0; pi < 4; ++pi) { qr[pi] = (f32x2){(float)r8[2 * pi], (float)r8[2 * pi + 1]}; qk[pi] = (f32x2){(float)k8[2 * pi], (float)k8[2 * pi + 1]};
;                           qv[2 * pi] = (float)v8[2 * pi]; qv[2 * pi + 1] = (float)v8[2 * pi + 1];
;                           const f32x2 tx = (f32x2){(float)w8[2 * pi], (float)w8[2 * pi + 1]} * 2.8853900817779268f;
;                           const f32x2 dn = (f32x2){__builtin_amdgcn_exp2f(tx[0]), __builtin_amdgcn_exp2f(tx[1])} + 1.f;
;                           const f32x2 th = (f32x2){__builtin_amdgcn_rcpf(dn[0]), __builtin_amdgcn_rcpf(dn[1])} * -2.f + 1.f;
;                           tw8[2 * pi] = (h16)th[0]; tw8[2 * pi + 1] = (h16)th[1]; }
;                       *(LAS h16x8*)(TWp + s_sub * 72 + c8) = tw8; *(LAS h16x8*)(QAp + s_sub * 72 + c8) = a8; }
;                     if (cn + 1 < SEQ / 32) SCAN_LOAD(cn + 1);
;                     LDS_WAIT();
;                     f32x4 accw[4], acca[4];
; #pragma unroll
;                     for (int ct = 0; ct < 4; ++ct) { accw[ct] = (f32x4){0.f, 0.f, 0.f, 0.f}; acca[ct] = (f32x4){0.f, 0.f, 0.f, 0.f}; }
; #pragma unroll
;                     for (int ks = 0; ks < 2; ++ks) {
;                         const h16x8 atw = *(const LAS h16x8*)(TWp + (lane & 7) * 72 + 32 * ks + 8 * (lane >> 4));
;                         const h16x8 aqa = *(const LAS h16x8*)(QAp + (lane & 7) * 72 + 32 * ks + 8 * (lane >> 4));
; #pragma unroll
;                         for (int ct = 0; ct < 4; ++ct) {
;                             const h16x8 bw = *(const LAS h16x8*)(w2T + (16 * ct + (lane & 15)) * 72 + 32 * ks + 8 * (lane >> 4));
.LBB0_610:
	s_waitcnt lgkmcnt(0)
	v_pk_fma_f16 v222, v95, s14, v99
	v_pk_fma_f16 v218, v96, s14, v100
	v_pk_fma_f16 v219, v97, s14, v101
	ds_read_b128 v[126:129], v173 offset:18432
	ds_read_b128 v[202:205], v173 offset:19584
	ds_read_b128 v[206:209], v183
	ds_read_b128 v[210:213], v183 offset:9216
	v_pk_fma_f16 v0, v94, s14, v98
	ds_read_b128 v[214:217], v183 offset:2304
	ds_read_b128 v[98:101], v183 offset:11520
	ds_read_b128 v[226:229], v183 offset:6912
	v_pk_fma_f16 v242, v69, v219, v97
	v_pk_fma_f16 v238, v68, v218, v96
	ds_read_b128 v[218:221], v183 offset:4608
	v_pk_fma_f16 v239, v3, v222, v95
	ds_read_b128 v[222:225], v183 offset:13824
	ds_read_b128 v[230:233], v183 offset:16128
	ds_read_b128 v[234:237], v173 offset:18496
	s_waitcnt lgkmcnt(8)
	v_mfma_f32_16x16x32_f16 v[206:209], v[126:129], v[206:209], 0
	v_pk_fma_f16 v0, v2, v0, v94
	v_pk_fma_f16 v94, v86, s14, v90
	v_pk_fma_f16 v95, v87, s14, v91
	s_waitcnt lgkmcnt(7)
	v_mfma_f32_16x16x32_f16 v[210:213], v[202:205], v[210:213], 0
	v_pk_fma_f16 v240, v61, v95, v87
	v_cvt_f32_f16_sdwa v87, v0 dst_sel:DWORD dst_unused:UNUSED_PAD src0_sel:WORD_1
	s_bitcmp1_b32 s81, 0
	s_waitcnt lgkmcnt(6)
	v_mfma_f32_16x16x32_f16 v[214:217], v[126:129], v[214:217], 0
	s_cselect_b32 s15, 0, 0xa800
	s_add_i32 s15, s15, 0
	s_waitcnt lgkmcnt(5)
	v_mfma_f32_16x16x32_f16 v[96:99], v[202:205], v[98:101], 0
	v_pk_fma_f16 v100, v88, s14, v92
	v_pk_fma_f16 v101, v89, s14, v93
	v_pk_fma_f16 v244, v70, v100, v88
	s_waitcnt lgkmcnt(3)
	v_mfma_f32_16x16x32_f16 v[218:221], v[126:129], v[218:221], 0
	v_pk_fma_f16 v243, v71, v101, v89
	v_pk_fma_f16 v101, v60, v94, v86
	v_cvt_f32_f16_e32 v86, v0
	s_waitcnt lgkmcnt(2)
	v_mfma_f32_16x16x32_f16 v[222:225], v[202:205], v[222:225], 0
	v_cvt_f32_f16_e32 v100, v101
	v_cvt_f32_f16_sdwa v101, v101 dst_sel:DWORD dst_unused:UNUSED_PAD src0_sel:WORD_1
	v_mfma_f32_16x16x32_f16 v[126:129], v[126:129], v[226:229], 0
	ds_read_b128 v[226:229], v173 offset:19648
	s_waitcnt lgkmcnt(2)
	v_mfma_f32_16x16x32_f16 v[202:205], v[202:205], v[230:233], 0
	s_waitcnt lgkmcnt(1)
	v_mfma_f32_16x16x32_f16 v[206:209], v[234:237], v[132:135], v[206:209]
	s_waitcnt lgkmcnt(0)
	v_mfma_f32_16x16x32_f16 v[210:213], v[226:229], v[136:139], v[210:213]
	v_mfma_f32_16x16x32_f16 v[214:217], v[234:237], v[164:167], v[214:217]
	v_cvt_f32_f16_e32 v88, v239
	v_cvt_f32_f16_sdwa v89, v239 dst_sel:DWORD dst_unused:UNUSED_PAD src0_sel:WORD_1
	s_nop 4
	v_cndmask_b32_e64 v0, v210, v206, s[4:5]
	s_waitcnt lgkmcnt(0)
	v_mfma_f32_16x16x32_f16 v[218:221], v[234:237], v[188:191], v[218:221]
	v_cndmask_b32_e64 v206, v212, v208, s[4:5]
	v_add_u32_e32 v208, 0x4800, v174
	v_mfma_f32_16x16x32_f16 v[96:99], v[226:229], v[184:187], v[96:99]
	v_cvt_f32_f16_e32 v94, v240
	v_cvt_f32_f16_sdwa v95, v240 dst_sel:DWORD dst_unused:UNUSED_PAD src0_sel:WORD_1
	s_waitcnt lgkmcnt(0)
	v_mfma_f32_16x16x32_f16 v[222:225], v[226:229], v[196:199], v[222:225]
	v_cvt_f32_f16_e32 v90, v238
	v_cvt_f32_f16_sdwa v91, v238 dst_sel:DWORD dst_unused:UNUSED_PAD src0_sel:WORD_1
	v_mfma_f32_16x16x32_f16 v[126:129], v[234:237], v[192:195], v[126:129]
	s_nop 0
	v_cndmask_b32_e64 v96, v96, v214, s[4:5]
	s_waitcnt lgkmcnt(0)
	v_cndmask_b32_e64 v93, v211, v207, s[4:5]
	s_waitcnt lgkmcnt(0)
	v_mfma_f32_16x16x32_f16 v[202:205], v[226:229], v[246:249], v[202:205]
	ds_write2_b32 v208, v0, v96 offset1:16
	v_cndmask_b32_e64 v0, v97, v215, s[4:5]
	ds_write2_b32 v208, v93, v0 offset0:64 offset1:80
	v_cndmask_b32_e64 v0, v98, v216, s[4:5]
	v_cndmask_b32_e64 v207, v213, v209, s[4:5]
	ds_write2_b32 v208, v206, v0 offset0:128 offset1:144
	v_cndmask_b32_e64 v0, v99, v217, s[4:5]
	ds_write2_b32 v208, v207, v0 offset0:192 offset1:208
	v_cndmask_b32_e64 v0, v222, v218, s[4:5]
	v_cndmask_b32_e64 v98, v202, v126, s[4:5]
	v_cndmask_b32_e64 v93, v223, v219, s[4:5]
	ds_write2_b32 v208, v0, v98 offset0:32 offset1:48
	v_cndmask_b32_e64 v0, v203, v127, s[4:5]
	v_cndmask_b32_e64 v96, v224, v220, s[4:5]
	ds_write2_b32 v208, v93, v0 offset0:96 offset1:112
	v_cndmask_b32_e64 v0, v204, v128, s[4:5]
	v_cndmask_b32_e64 v97, v225, v221, s[4:5]
	ds_write2_b32 v208, v96, v0 offset0:160 offset1:176
	v_cndmask_b32_e64 v0, v205, v129, s[4:5]
	ds_write2_b32 v208, v97, v0 offset0:224 offset1:240
	s_waitcnt lgkmcnt(0)
	ds_read_b128 v[126:129], v200 offset:20480
	ds_read_b128 v[206:209], v200 offset:20496
	v_pk_mul_f32 v[212:213], v[40:41], v[100:101]
	v_pk_mul_f32 v[218:219], v[42:43], v[94:95]
	ds_read_b128 v[96:99], v200 offset:18432
	ds_read_b128 v[202:205], v200 offset:18448
	s_waitcnt lgkmcnt(3)
	v_pk_add_f32 v[126:127], v[32:33], v[126:127]
	s_waitcnt lgkmcnt(2)
	v_pk_add_f32 v[208:209], v[30:31], v[208:209]
	v_pk_mul_f32 v[126:127], v[126:127], s[36:37] op_sel_hi:[1,0]
	v_cvt_f32_f16_e32 v230, v244
	v_exp_f32_e32 v126, v126
	v_exp_f32_e32 v127, v127
	v_cvt_f32_f16_sdwa v231, v244 dst_sel:DWORD dst_unused:UNUSED_PAD src0_sel:WORD_1
	v_pk_mul_f32 v[208:209], v[208:209], s[36:37] op_sel_hi:[1,0]
	v_cvt_f32_f16_e32 v210, v243
	v_pk_add_f32 v[126:127], v[126:127], 1.0 op_sel_hi:[1,0]
	v_exp_f32_e32 v208, v208
	v_rcp_f32_e32 v214, v126
	v_rcp_f32_e32 v215, v127
	v_exp_f32_e32 v209, v209
	v_cvt_f32_f16_sdwa v211, v243 dst_sel:DWORD dst_unused:UNUSED_PAD src0_sel:WORD_1
	s_waitcnt lgkmcnt(1)
; #define LAS __attribute__((address_space(3)))
; __device__ __forceinline__ void phase_scan(const Params& p, LAS unsigned char* lds) {
;     ...
;                     f32x2 kk[4], av_[4], kp[4], dec[4], kn2 = {0.f, 0.f}, sb2 = {0.f, 0.f};
; #pragma unroll
;                     for (int pi = 0; pi < 4; ++pi) {
;                         const f32x2 zw = (pi < 2 ? (f32x2){zw0[2 * pi], zw0[2 * pi + 1]} : (f32x2){zw1[2 * pi - 4], zw1[2 * pi - 3]}) + w0r[pi];
;                         const f32x2 za = (pi < 2 ? (f32x2){za0[2 * pi], za0[2 * pi + 1]} : (f32x2){za1[2 * pi - 4], za1[2 * pi - 3]}) + a0r[pi];
;                         const f32x2 tw_ = zw * -1.4426950408889634f, ta_ = za * -1.4426950408889634f;
;                         const f32x2 dw = (f32x2){__builtin_amdgcn_exp2f(tw_[0]), __builtin_amdgcn_exp2f(tw_[1])} + 1.f, da = (f32x2){__builtin_amdgcn_exp2f(ta_[0]), __builtin_amdgcn_exp2f(ta_[1])} + 1.f;
;                         const f32x2 sw = (f32x2){__builtin_amdgcn_rcpf(dw[0]), __builtin_amdgcn_rcpf(dw[1])} * -0.8750387749225136f;
;                         dec[pi] = (f32x2){__builtin_amdgcn_exp2f(sw[0]), __builtin_amdgcn_exp2f(sw[1])};
;                         av_[pi] = (f32x2){__builtin_amdgcn_rcpf(da[0]), __builtin_amdgcn_rcpf(da[1])};
;                         kk[pi] = qk[pi] * kkr[pi]; kn2 = kk[pi] * kk[pi] + kn2;
;                         kp[pi] = qk[pi] * (av_[pi] * kar[pi] + omk[pi]);
;                         sb2 = (qr[pi] * kp[pi]) * rkr[pi] + sb2; }
;                     const float kn = red8(kn2[0] + kn2[1]), sbn = red8(sb2[0] + sb2[1]);
;                     const float ninv = -rsqrtf(fmaxf(kn, 1e-12f));
;                     LAS float* dR = OPS + (cn & 1) * SET_F + s_l * 64 + c8;
; #pragma unroll
;                     for (int hf = 0; hf < 2; ++hf) {
;                         const f32x2 na0 = kk[2 * hf] * ninv, na1 = kk[2 * hf + 1] * ninv;
;                         const f32x2 nb0 = na0 * av_[2 * hf], nb1 = na1 * av_[2 * hf + 1];
;                         *(LAS f32x4*)(dR + 4 * hf) = (f32x4){qr[2 * hf][0], qr[2 * hf][1], qr[2 * hf + 1][0], qr[2 * hf + 1][1]};
;                         *(LAS f32x4*)(dR + 2048 + 4 * hf) = (f32x4){dec[2 * hf][0], dec[2 * hf][1], dec[2 * hf + 1][0], dec[2 * hf + 1][1]};
;                         *(LAS f32x4*)(dR + 4096 + 4 * hf) = (f32x4){kp[2 * hf][0], kp[2 * hf][1], kp[2 * hf + 1][0], kp[2 * hf + 1][1]};
	v_pk_add_f32 v[96:97], v[24:25], v[96:97]
	v_pk_fma_f32 v[126:127], v[48:49], v[214:215], v[154:155]
	v_pk_add_f32 v[98:99], v[26:27], v[98:99]
	v_pk_mul_f32 v[126:127], v[126:127], v[100:101]
	v_pk_add_f32 v[100:101], v[34:35], v[128:129]
	v_pk_mul_f32 v[128:129], v[126:127], v[86:87]
	v_pk_mul_f32 v[100:101], v[100:101], s[36:37] op_sel_hi:[1,0]
	v_pk_fma_f32 v[216:217], v[56:57], v[128:129], 0 op_sel_hi:[1,1,0]
	v_exp_f32_e32 v100, v100
	v_exp_f32_e32 v101, v101
	v_pk_mul_f32 v[128:129], v[218:219], v[218:219]
	v_pk_mul_f32 v[224:225], v[36:37], v[230:231]
	v_pk_fma_f32 v[220:221], v[212:213], v[212:213], v[128:129]
	v_pk_add_f32 v[100:101], v[100:101], 1.0 op_sel_hi:[1,0]
	v_pk_mul_f32 v[96:97], v[96:97], s[36:37] op_sel_hi:[1,0]
	v_rcp_f32_e32 v100, v100
	v_rcp_f32_e32 v101, v101
	v_pk_mul_f32 v[98:99], v[98:99], s[36:37] op_sel_hi:[1,0]
	v_pk_add_f32 v[208:209], v[208:209], 1.0 op_sel_hi:[1,0]
	v_exp_f32_e32 v96, v96
	v_pk_fma_f32 v[128:129], v[50:51], v[100:101], v[156:157]
	v_exp_f32_e32 v97, v97
	v_pk_mul_f32 v[128:129], v[128:129], v[94:95]
	v_pk_add_f32 v[94:95], v[28:29], v[206:207]
	v_pk_mul_f32 v[206:207], v[128:129], v[88:89]
	v_pk_mul_f32 v[94:95], v[94:95], s[36:37] op_sel_hi:[1,0]
	v_pk_fma_f32 v[216:217], v[58:59], v[206:207], v[216:217]
	v_exp_f32_e32 v94, v94
	v_exp_f32_e32 v95, v95
	v_exp_f32_e32 v98, v98
	v_exp_f32_e32 v99, v99
	v_pk_mul_f32 v[226:227], v[38:39], v[210:211]
	v_pk_add_f32 v[94:95], v[94:95], 1.0 op_sel_hi:[1,0]
	s_waitcnt lgkmcnt(0)
	v_pk_add_f32 v[202:203], v[20:21], v[202:203]
	v_rcp_f32_e32 v222, v94
	v_rcp_f32_e32 v223, v95
	v_pk_fma_f32 v[94:95], v[224:225], v[224:225], v[220:221]
	v_pk_add_f32 v[204:205], v[22:23], v[204:205]
	v_pk_fma_f32 v[94:95], v[226:227], v[226:227], v[94:95]
	v_pk_fma_f32 v[206:207], v[44:45], v[222:223], v[158:159]
	v_cvt_f32_f16_e32 v92, v242
	v_pk_mul_f32 v[206:207], v[206:207], v[230:231]
	v_cvt_f32_f16_sdwa v93, v242 dst_sel:DWORD dst_unused:UNUSED_PAD src0_sel:WORD_1
	v_pk_mul_f32 v[220:221], v[206:207], v[90:91]
	v_pk_mul_f32 v[202:203], v[202:203], s[36:37] op_sel_hi:[1,0]
	v_pk_fma_f32 v[216:217], v[52:53], v[220:221], v[216:217]
	v_rcp_f32_e32 v220, v208
	v_rcp_f32_e32 v221, v209
	v_pk_mul_f32 v[204:205], v[204:205], s[36:37] op_sel_hi:[1,0]
	v_add_f32_e32 v0, v94, v95
	v_exp_f32_e32 v202, v202
	v_exp_f32_e32 v203, v203
	v_exp_f32_e32 v204, v204
	v_exp_f32_e32 v205, v205
	v_add_f32_dpp v0, v0, v0 quad_perm:[1,0,3,2] row_mask:0xf bank_mask:0xf bound_ctrl:1
	v_pk_add_f32 v[96:97], v[96:97], 1.0 op_sel_hi:[1,0]
	v_pk_add_f32 v[98:99], v[98:99], 1.0 op_sel_hi:[1,0]
	v_pk_fma_f32 v[208:209], v[46:47], v[220:221], v[160:161]
	v_add_f32_dpp v0, v0, v0 quad_perm:[2,3,0,1] row_mask:0xf bank_mask:0xf bound_ctrl:1
	v_rcp_f32_e32 v96, v96
	v_rcp_f32_e32 v97, v97
	v_rcp_f32_e32 v98, v98
	v_rcp_f32_e32 v99, v99
	v_pk_mul_f32 v[208:209], v[208:209], v[210:211]
	v_add_f32_dpp v95, v0, v0 row_half_mirror row_mask:0xf bank_mask:0xf bound_ctrl:1
	v_pk_mul_f32 v[210:211], v[208:209], v[92:93]
	v_max_f32_e32 v95, 0x2b8cbccc, v95
	v_pk_add_f32 v[202:203], v[202:203], 1.0 op_sel_hi:[1,0]
	v_pk_add_f32 v[204:205], v[204:205], 1.0 op_sel_hi:[1,0]
	v_pk_fma_f32 v[210:211], v[54:55], v[210:211], v[216:217]
	v_rsq_f32_e32 v216, v95
	v_rcp_f32_e32 v202, v202
	v_rcp_f32_e32 v203, v203
	v_rcp_f32_e32 v204, v204
	v_rcp_f32_e32 v205, v205
	v_pk_mul_f32 v[96:97], v[96:97], s[38:39] op_sel_hi:[1,0]
	v_pk_mul_f32 v[98:99], v[98:99], s[38:39] op_sel_hi:[1,0]
	v_add3_u32 v95, s15, v175, v144
	v_exp_f32_e32 v96, v96
	v_exp_f32_e32 v97, v97
	v_exp_f32_e32 v98, v98
	v_exp_f32_e32 v99, v99
	v_add_u32_e32 v217, 0x8800, v95
	v_add_f32_e32 v0, v210, v211
	v_pk_mul_f32 v[210:211], v[212:213], v[216:217] op_sel_hi:[1,0] neg_lo:[0,1] neg_hi:[0,1]
	v_pk_mul_f32 v[212:213], v[218:219], v[216:217] op_sel_hi:[1,0] neg_lo:[0,1] neg_hi:[0,1]
	v_pk_mul_f32 v[202:203], v[202:203], s[38:39] op_sel_hi:[1,0]
	v_pk_mul_f32 v[204:205], v[204:205], s[38:39] op_sel_hi:[1,0]
	v_pk_mul_f32 v[100:101], v[212:213], v[100:101]
	s_waitcnt lgkmcnt(0)
	v_exp_f32_e32 v202, v202
	v_exp_f32_e32 v203, v203
	v_exp_f32_e32 v204, v204
	v_exp_f32_e32 v205, v205
	ds_write_b128 v95, v[86:89] offset:34816
	ds_write_b128 v95, v[96:99] offset:43008
	ds_write_b128 v95, v[126:129] offset:51200
	ds_write_b128 v95, v[210:213] offset:59392
	v_pk_mul_f32 v[86:87], v[210:211], v[214:215] neg_lo:[0,1] neg_hi:[0,1]
	v_xor_b32_e32 v88, 0x80000000, v100
	v_xor_b32_e32 v89, 0x80000000, v101
	v_add_f32_dpp v0, v0, v0 quad_perm:[1,0,3,2] row_mask:0xf bank_mask:0xf bound_ctrl:1
	ds_write_b128 v217, v[86:89] offset:32768
	v_pk_mul_f32 v[88:89], v[226:227], v[216:217] op_sel_hi:[1,0] neg_lo:[0,1] neg_hi:[0,1]
	v_add_f32_dpp v0, v0, v0 quad_perm:[2,3,0,1] row_mask:0xf bank_mask:0xf bound_ctrl:1
	v_mov_b32_e32 v94, 0
	v_pk_mul_f32 v[86:87], v[224:225], v[216:217] op_sel_hi:[1,0] neg_lo:[0,1] neg_hi:[0,1]
	v_pk_mul_f32 v[96:97], v[88:89], v[220:221]
	v_mov_b32_dpp v94, v0 row_half_mirror row_mask:0xf bank_mask:0xf
	ds_write_b128 v95, v[90:93] offset:34832
	ds_write_b128 v95, v[202:205] offset:43024
	ds_write_b128 v95, v[206:209] offset:51216
	ds_write_b128 v95, v[86:89] offset:59408
	v_pk_mul_f32 v[86:87], v[86:87], v[222:223] neg_lo:[0,1] neg_hi:[0,1]
	v_xor_b32_e32 v88, 0x80000000, v96
	v_xor_b32_e32 v89, 0x80000000, v97
	ds_write_b128 v217, v[86:89] offset:32784
	s_and_saveexec_b64 s[56:57], s[10:11]
	s_cbranch_execz .LBB0_612
	v_pk_fma_f16 v82, v78, s14, v82
	v_pk_fma_f16 v83, v79, s14, v83
	v_pk_fma_f16 v78, v62, v82, v78
	v_pk_fma_f16 v84, v80, s14, v84
	v_pk_fma_f16 v79, v63, v83, v79
	v_cvt_f32_f16_e32 v82, v78
	v_cvt_f32_f16_sdwa v78, v78 dst_sel:DWORD dst_unused:UNUSED_PAD src0_sel:WORD_1
	s_add_i32 s15, s15, 0x8800
	v_pk_fma_f16 v85, v81, s14, v85
	v_pk_fma_f16 v80, v72, v84, v80
	v_cvt_f32_f16_e32 v83, v79
	v_cvt_f32_f16_sdwa v79, v79 dst_sel:DWORD dst_unused:UNUSED_PAD src0_sel:WORD_1
	v_lshlrev_b32_e32 v86, 2, v169
	v_pk_fma_f16 v81, v73, v85, v81
	v_cvt_f32_f16_e32 v84, v80
	v_cvt_f32_f16_sdwa v80, v80 dst_sel:DWORD dst_unused:UNUSED_PAD src0_sel:WORD_1
	v_add3_u32 v86, s15, v201, v86
	v_cvt_f32_f16_e32 v85, v81
	v_cvt_f32_f16_sdwa v81, v81 dst_sel:DWORD dst_unused:UNUSED_PAD src0_sel:WORD_1
	v_add_u32_e32 v86, 0xa000, v86
	ds_write2_b32 v86, v82, v78 offset1:32
	ds_write2_b32 v86, v83, v79 offset0:64 offset1:96
	ds_write2_b32 v86, v84, v80 offset0:128 offset1:160
	ds_write2_b32 v86, v85, v81 offset0:192 offset1:224
